# S5 Win and MW matrices stored in MFMA fragment order (each B/A fragment load is one contiguous 1 KB instead of 32 rows x 32 B)
# baseline (speedup 1.0000x reference)
; __device__ __forceinline__ unsigned cvt_pk_bf16(float lo, float hi) { unsigned r; asm("v_cvt_pk_bf16_f32 %0, %1, %2" : "=v"(r) : "v"(lo), "v"(hi)); return r; }
; __device__ __forceinline__ void p0_s5_group(const Args& a, LAS unsigned char* lds, int g, int tid) {
;     ...
;         u32x4 o; o.x = cvt_pk_bf16(v[0], v[1]); o.y = cvt_pk_bf16(v[2], v[3]); o.z = cvt_pk_bf16(v[4], v[5]); o.w = cvt_pk_bf16(v[6], v[7]);
;         *(u32x4*)(MW + (size_t)rr * 384 + cg * 8) = o;
.LBB0_117:
	s_or_b64 exec, exec, s[4:5]
	v_lshrrev_b32_e32 v66, 5, v2
	v_and_b32_e32 v67, 31, v2
	v_mul_u32_u24_e32 v66, 0x600, v66
	v_add_u32_e32 v66, v66, v67
	v_lshrrev_b32_e32 v67, 4, v52
	v_lshl_add_u32 v66, v67, 6, v66
	v_bfe_u32 v67, v52, 3, 1
	v_lshl_add_u32 v66, v67, 5, v66
	v_lshlrev_b32_e32 v2, 4, v66
	v_mov_b32_e32 v52, 0
	s_movk_i32 s4, 0x2dff
	v_cvt_pk_bf16_f32 v62, v53, v48
	v_cvt_pk_bf16_f32 v63, v55, v54
	v_lshl_add_u64 v[54:55], s[16:17], 0, v[2:3]
	v_mov_b32_e32 v53, v3
	v_add_u32_e32 v2, 0x200, v39
	v_cmp_lt_u32_e32 vcc, s4, v39
	v_lshl_add_u64 v[52:53], v[52:53], 1, v[54:55]
	s_or_b64 s[96:97], vcc, s[96:97]
	v_mov_b32_e32 v39, v2
	v_cvt_pk_bf16_f32 v64, v58, v57
	v_cvt_pk_bf16_f32 v65, v59, v60
	global_store_dwordx4 v[52:53], v[62:65], off sc1
	s_andn2_b64 exec, exec, s[96:97]
	s_cbranch_execz .LBB0_137

; __device__ __forceinline__ unsigned cvt_pk_bf16(float lo, float hi) { unsigned r; asm("v_cvt_pk_bf16_f32 %0, %1, %2" : "=v"(r) : "v"(lo), "v"(hi)); return r; }
; __device__ __forceinline__ void p0_s5_group(const Args& a, LAS unsigned char* lds, int g, int tid) {
;     ...
;     for (int idx = tid; idx < 128 * 32; idx += NWAVES * 64) {
;         const int n = idx >> 5, cg = idx & 31, p = n & 63, im = n >> 6, sp = cg >> 1, c0 = (cg & 1) * 8;
;         const float lr = LPre[(15 - sp) * 64 + p], li = LPim[(15 - sp) * 64 + p];
;         float v[8];
; #pragma unroll
;         for (int i = 0; i < 8; ++i) { const float br = BBre[p * 16 + c0 + i], bi = BBim[p * 16 + c0 + i]; v[i] = im ? (lr * bi + li * br) : (lr * br - li * bi); }
;         u32x4 o; o.x = cvt_pk_bf16(v[0], v[1]); o.y = cvt_pk_bf16(v[2], v[3]); o.z = cvt_pk_bf16(v[4], v[5]); o.w = cvt_pk_bf16(v[6], v[7]);
;         *(u32x4*)(Win + (size_t)n * 256 + cg * 8) = o;
;     }
.LBB0_138:
	v_and_b32_e32 v56, 8, v39
	v_and_b32_e32 v55, 63, v2
	s_movk_i32 s4, 0x3c0
	v_lshlrev_b32_e32 v56, 2, v56
	v_bitop3_b32 v57, v48, s4, v55 bitop3:0x26
	v_lshl_or_b32 v55, v55, 6, v56
	v_lshl_add_u32 v57, v57, 2, 0
	v_add_u32_e32 v55, 0, v55
	ds_read2st64_b32 v[88:89], v57 offset1:17
	ds_read_b128 v[56:59], v55 offset:8704
	ds_read_b128 v[60:63], v55 offset:8720
	ds_read_b128 v[64:67], v55 offset:12800
	s_movk_i32 s4, 0x800
	v_cmp_gt_u32_e32 vcc, s4, v54
	s_waitcnt lgkmcnt(2)
	v_mov_b32_e32 v92, v56
	v_mov_b32_e32 v90, v89
	v_mov_b32_e32 v91, v88
	s_waitcnt lgkmcnt(0)
	v_mov_b32_e32 v93, v64
	v_pk_mul_f32 v[94:95], v[90:91], v[92:93]
	v_pk_mul_f32 v[92:93], v[88:89], v[92:93]
	v_add_f32_e32 v56, v94, v95
	v_sub_f32_e32 v64, v92, v93
	v_cndmask_b32_e32 v87, v56, v64, vcc
	v_mov_b32_e32 v64, v57
	v_pk_mul_f32 v[56:57], v[90:91], v[64:65]
	s_mov_b64 s[4:5], 0x2000
	v_add_f32_e32 v92, v56, v57
	v_pk_mul_f32 v[56:57], v[88:89], v[64:65]
	v_add_u32_e32 v48, 0x4000, v48
	v_sub_f32_e32 v56, v56, v57
	v_cndmask_b32_e32 v92, v92, v56, vcc
	v_mov_b32_e32 v56, v58
	v_mov_b32_e32 v57, v66
	v_pk_mul_f32 v[64:65], v[90:91], v[56:57]
	v_pk_mul_f32 v[56:57], v[88:89], v[56:57]
	v_add_f32_e32 v58, v64, v65
	v_sub_f32_e32 v56, v56, v57
	v_mov_b32_e32 v66, v59
	v_cndmask_b32_e32 v93, v58, v56, vcc
	v_pk_mul_f32 v[56:57], v[90:91], v[66:67]
	v_mov_b32_e32 v64, v60
	v_add_f32_e32 v58, v56, v57
	v_pk_mul_f32 v[56:57], v[88:89], v[66:67]
	v_add_u32_e32 v39, 0x1000, v39
	v_sub_f32_e32 v56, v56, v57
	v_cndmask_b32_e32 v94, v58, v56, vcc
	ds_read_b128 v[56:59], v55 offset:12816
	v_add_u32_e32 v2, 16, v2
	s_waitcnt lgkmcnt(0)
	v_mov_b32_e32 v65, v56
	v_pk_mul_f32 v[66:67], v[90:91], v[64:65]
	v_pk_mul_f32 v[64:65], v[88:89], v[64:65]
	v_add_f32_e32 v55, v66, v67
	v_sub_f32_e32 v56, v64, v65
	v_cndmask_b32_e32 v55, v55, v56, vcc
	v_mov_b32_e32 v56, v61
	v_pk_mul_f32 v[60:61], v[90:91], v[56:57]
	v_pk_mul_f32 v[56:57], v[88:89], v[56:57]
	v_add_f32_e32 v60, v60, v61
	v_sub_f32_e32 v56, v56, v57
	v_cndmask_b32_e32 v64, v60, v56, vcc
	v_mov_b32_e32 v56, v62
	v_mov_b32_e32 v57, v58
	v_pk_mul_f32 v[60:61], v[90:91], v[56:57]
	v_pk_mul_f32 v[56:57], v[88:89], v[56:57]
	v_add_f32_e32 v58, v60, v61
	v_sub_f32_e32 v56, v56, v57
	v_cndmask_b32_e32 v60, v58, v56, vcc
	v_mov_b32_e32 v58, v63
	v_pk_mul_f32 v[56:57], v[90:91], v[58:59]
	s_nop 0
	v_add_f32_e32 v61, v56, v57
	v_pk_mul_f32 v[56:57], v[88:89], v[58:59]
	v_cvt_pk_bf16_f32 v58, v55, v64
	v_add_u32_e32 v55, 0x200, v54
	v_sub_f32_e32 v56, v56, v57
	v_cndmask_b32_e32 v59, v61, v56, vcc
	v_cvt_pk_bf16_f32 v56, v87, v92
	v_cvt_pk_bf16_f32 v57, v93, v94
	v_cvt_pk_bf16_f32 v59, v60, v59
	v_lshrrev_b32_e32 v60, 10, v54
	v_bfe_u32 v61, v54, 1, 4
	v_bfe_u32 v62, v54, 5, 5
	v_and_b32_e32 v63, 1, v54
	v_lshl_or_b32 v62, v63, 5, v62
	v_lshl_or_b32 v62, v61, 6, v62
	v_lshl_or_b32 v62, v60, 10, v62
	v_sub_u32_e32 v62, v62, v54
	v_ashrrev_i32_e32 v63, 31, v62
	v_lshl_add_u64 v[60:61], v[62:63], 4, v[52:53]
	global_store_dwordx4 v[60:61], v[56:59], off sc1
	v_lshl_add_u64 v[52:53], v[52:53], 0, s[4:5]
	s_movk_i32 s4, 0xdff
	v_cmp_lt_u32_e32 vcc, s4, v54
	s_or_b64 s[16:17], vcc, s[16:17]
	v_mov_b32_e32 v54, v55
	s_andn2_b64 exec, exec, s[16:17]
	s_cbranch_execnz .LBB0_138
	s_or_b64 exec, exec, s[16:17]
	s_and_saveexec_b64 s[4:5], s[14:15]
	s_cbranch_execz .LBB0_141
	ds_read2st64_b32 v[52:53], v71 offset0:1 offset1:16
	ds_read2st64_b32 v[54:55], v71 offset0:18 offset1:33
	s_mul_i32 s16, s94, 0x2400
	s_mul_hi_i32 s17, s94, 0x2400
	s_add_u32 s16, s33, s16
	s_addc_u32 s17, s34, s17
	v_lshlrev_b32_e32 v2, 2, v0
	s_waitcnt lgkmcnt(1)
	global_store_dword v2, v52, s[16:17]
	s_waitcnt lgkmcnt(0)
	global_store_dword v2, v54, s[16:17] offset:256
	global_store_dword v2, v53, s[16:17] offset:512
	global_store_dword v2, v55, s[16:17] offset:768

; __device__ __forceinline__ void s5_prompt(const Args& a, LAS unsigned char* lds, int b, int g, int tid, int lane, int wave) {
;     ...
;         const int mt = wave & 3, nt0 = (wave >> 2) * 2;
;         const bf16_t* w0 = Win + (size_t)(32 * nt0 + r32) * 256 + 8 * hh;
;         bf16x8 bw[2][16];
;         {
;             u32x4 v[8];
; #pragma unroll
;             for (int i = 0; i < 8; ++i) { const int q = tid + 512 * i, t = q >> 1, half = q & 1; v[i] = *(const u32x4*)(U + (size_t)(b * SEQ + t) * DH + 16 * g + 8 * half); }
; #pragma unroll
;             for (int ks = 0; ks < 16; ++ks) { bw[0][ks] = *(const bf16x8*)(w0 + 16 * ks); bw[1][ks] = *(const bf16x8*)(w0 + 32 * 256 + 16 * ks); }
;             asm volatile("" ::: "memory");
.LBB0_559:
	s_lshl_b32 s0, s35, 3
	s_and_b32 s0, s0, 56
	s_bfe_u32 s1, s35, 0x30003
	s_or_b32 s36, s0, s1
	s_lshl_b32 s0, s36, 18
	s_add_u32 s0, s13, s0
	s_addc_u32 s1, s28, 0
	s_add_u32 s6, s0, 0x10000
	s_addc_u32 s7, s1, 0
	s_lshl_b32 s37, s35, 5
	s_and_b32 s37, s37, 0xfffff800
	s_mul_i32 s44, s36, 0x2400
	v_or_b32_e32 v2, s37, v162
	v_or_b32_e32 v6, s37, v185
	v_or_b32_e32 v8, s37, v186
	v_or_b32_e32 v14, s37, v187
	v_or_b32_e32 v16, s37, v188
	v_or_b32_e32 v22, s37, v189
	v_or_b32_e32 v24, s37, v190
	v_lshl_add_u64 v[36:37], v[168:169], 0, s[44:45]
	s_lshl_b32 s44, s36, 5
	v_ashrrev_i32_e32 v3, 31, v2
	v_ashrrev_i32_e32 v7, 31, v6
	v_ashrrev_i32_e32 v9, 31, v8
	v_ashrrev_i32_e32 v15, 31, v14
	v_ashrrev_i32_e32 v17, 31, v16
	v_ashrrev_i32_e32 v23, 31, v22
	v_ashrrev_i32_e32 v25, 31, v24
	v_lshl_add_u64 v[30:31], v[172:173], 0, s[44:45]
	v_lshlrev_b64 v[2:3], 11, v[2:3]
	v_lshlrev_b64 v[6:7], 11, v[6:7]
	v_lshlrev_b64 v[8:9], 11, v[8:9]
	v_lshlrev_b64 v[14:15], 11, v[14:15]
	v_lshlrev_b64 v[16:17], 11, v[16:17]
	v_lshlrev_b64 v[22:23], 11, v[22:23]
	v_lshlrev_b64 v[24:25], 11, v[24:25]
	v_lshl_add_u64 v[2:3], v[30:31], 0, v[2:3]
	v_lshl_add_u64 v[6:7], v[30:31], 0, v[6:7]
	v_lshl_add_u64 v[10:11], v[30:31], 0, v[8:9]
	v_lshl_add_u64 v[14:15], v[30:31], 0, v[14:15]
	v_lshl_add_u64 v[18:19], v[30:31], 0, v[16:17]
	v_lshl_add_u64 v[22:23], v[30:31], 0, v[22:23]
	v_lshl_add_u64 v[26:27], v[30:31], 0, v[24:25]
	global_load_dwordx4 v[2:5], v[2:3], off
	s_nop 0
	global_load_dwordx4 v[6:9], v[6:7], off
	s_nop 0
	global_load_dwordx4 v[10:13], v[10:11], off
	s_nop 0
	global_load_dwordx4 v[14:17], v[14:15], off
	s_nop 0
	global_load_dwordx4 v[18:21], v[18:19], off
	s_nop 0
	global_load_dwordx4 v[22:25], v[22:23], off
	s_nop 0
	global_load_dwordx4 v[26:29], v[26:27], off
	v_or_b32_e32 v32, s37, v191
	v_ashrrev_i32_e32 v33, 31, v32
	v_lshlrev_b64 v[32:33], 11, v[32:33]
	v_lshl_add_u64 v[30:31], v[30:31], 0, v[32:33]
	global_load_dwordx4 v[30:33], v[30:31], off
	v_lshlrev_b32_e32 v35, 4, v210
	v_lshrrev_b32_e32 v158, 8, v0
	v_lshl_add_u32 v35, v158, 15, v35
	s_mov_b64 s[98:99], s[0:1]
	s_add_u32 s100, s0, 0x4000
	s_addc_u32 s101, s1, 0
	global_load_dwordx4 v[38:41], v35, s[98:99]
	global_load_dwordx4 v[42:45], v35, s[100:101]
	global_load_dwordx4 v[46:49], v35, s[98:99] offset:1024
	global_load_dwordx4 v[50:53], v35, s[100:101] offset:1024
	global_load_dword v34, v[36:37], off offset:512
	global_load_dword v36, v[36:37], off offset:768
	global_load_dwordx4 v[54:57], v35, s[98:99] offset:2048
	global_load_dwordx4 v[58:61], v35, s[100:101] offset:2048
	global_load_dwordx4 v[62:65], v35, s[98:99] offset:3072
	s_add_u32 s98, s98, 0x1000
	s_addc_u32 s99, s99, 0
	global_load_dwordx4 v[66:69], v35, s[98:99]
	global_load_dwordx4 v[70:73], v35, s[100:101] offset:3072
	s_add_u32 s100, s100, 0x1000
	s_addc_u32 s101, s101, 0
	global_load_dwordx4 v[74:77], v35, s[100:101]
	global_load_dwordx4 v[78:81], v35, s[98:99] offset:1024
	global_load_dwordx4 v[82:85], v35, s[98:99] offset:2048
	global_load_dwordx4 v[86:89], v35, s[100:101] offset:1024
	global_load_dwordx4 v[90:93], v35, s[100:101] offset:2048
	global_load_dwordx4 v[94:97], v35, s[98:99] offset:3072
	s_add_u32 s98, s98, 0x1000
	s_addc_u32 s99, s99, 0
	global_load_dwordx4 v[98:101], v35, s[98:99]
	global_load_dwordx4 v[102:105], v35, s[100:101] offset:3072
	s_add_u32 s100, s100, 0x1000
	s_addc_u32 s101, s101, 0
	global_load_dwordx4 v[106:109], v35, s[100:101]
	global_load_dwordx4 v[110:113], v35, s[98:99] offset:1024
	global_load_dwordx4 v[114:117], v35, s[98:99] offset:2048
	global_load_dwordx4 v[118:121], v35, s[100:101] offset:1024
	global_load_dwordx4 v[122:125], v35, s[100:101] offset:2048
	global_load_dwordx4 v[126:129], v35, s[98:99] offset:3072
	s_add_u32 s98, s98, 0x1000
	s_addc_u32 s99, s99, 0
	global_load_dwordx4 v[130:133], v35, s[98:99]
	global_load_dwordx4 v[134:137], v35, s[100:101] offset:3072
	s_add_u32 s100, s100, 0x1000
	s_addc_u32 s101, s101, 0
	global_load_dwordx4 v[138:141], v35, s[100:101]
	global_load_dwordx4 v[142:145], v35, s[98:99] offset:1024
	global_load_dwordx4 v[146:149], v35, s[98:99] offset:2048
	global_load_dwordx4 v[150:153], v35, s[100:101] offset:1024
	global_load_dwordx4 v[154:157], v35, s[100:101] offset:2048
	global_load_dwordx4 v[158:161], v35, s[98:99] offset:3072
	global_load_dwordx4 v[178:181], v35, s[100:101] offset:3072
	s_andn2_b64 vcc, exec, s[68:69]
	s_waitcnt vmcnt(41)
	ds_write_b128 v199, v[2:5]
	s_waitcnt vmcnt(40)
	ds_write_b128 v200, v[6:9]
	s_waitcnt vmcnt(39)
	ds_write_b128 v201, v[10:13]
	s_waitcnt vmcnt(38)
	ds_write_b128 v202, v[14:17]
	s_waitcnt vmcnt(37)
	ds_write_b128 v203, v[18:21]
	s_waitcnt vmcnt(36)
	ds_write_b128 v204, v[22:25]
	s_waitcnt vmcnt(35)
	ds_write_b128 v205, v[26:29]
	s_waitcnt vmcnt(34)
	ds_write_b128 v206, v[30:33]
	s_waitcnt lgkmcnt(0)
	s_barrier
; #define LAS __attribute__((address_space(3)))
; #define MFMA32(a, b, c) __builtin_amdgcn_mfma_f32_32x32x16_bf16((a), (b), (c), 0, 0, 0)
; __device__ __forceinline__ void s5_prompt(const Args& a, LAS unsigned char* lds, int b, int g, int tid, int lane, int wave) {
;     ...
;         const LAS unsigned char* xa = XCs + (32 * mt + r32) * S5_PITCH + 16 * hh;
; #pragma unroll
;         for (int ks = 0; ks < 16; ++ks) { const bf16x8 af = *(const LAS bf16x8*)(xa + 32 * ks); acc0 = MFMA32(af, bw[0][ks], acc0); acc1 = MFMA32(af, bw[1][ks], acc1); }
;         LAS float* Z = (LAS float*)ZS;
; #pragma unroll
;         for (int i = 0; i < 16; ++i) { const int j = 32 * mt + (i & 3) + 8 * (i >> 2) + 4 * hh;
;             Z[j * (S5_PITCH / 4) + 32 * nt0 + r32] = acc0[i]; Z[j * (S5_PITCH / 4) + 32 * nt0 + 32 + r32] = acc1[i]; }
;     }
;     __syncthreads();
;     bf16x8 am[24];
;     { const int mt = wave; const bf16_t* mw = MW + (size_t)(32 * mt + r32) * 384 + 8 * hh;
; #pragma unroll
;       for (int ks = 0; ks < 16; ++ks) if (ks < 2 * mt + 2) am[ks] = *(const bf16x8*)(mw + 16 * ks);
; #pragma unroll
;       for (int kq = 0; kq < 8; ++kq) am[16 + kq] = *(const bf16x8*)(mw + 256 + 16 * kq); }
	ds_read_b128 v[18:21], v207
	s_waitcnt vmcnt(33) lgkmcnt(0)
	v_mfma_f32_32x32x16_bf16 v[2:17], v[18:21], v[38:41], 0
	ds_read_b128 v[38:41], v207 offset:32
	s_waitcnt vmcnt(32)
	v_mfma_f32_32x32x16_bf16 v[18:33], v[18:21], v[42:45], 0
	s_waitcnt vmcnt(31) lgkmcnt(0)
	v_mfma_f32_32x32x16_bf16 v[2:17], v[38:41], v[46:49], v[2:17]
	s_waitcnt vmcnt(30)
	v_mfma_f32_32x32x16_bf16 v[18:33], v[38:41], v[50:53], v[18:33]
	ds_read_b128 v[38:41], v207 offset:64
	s_waitcnt vmcnt(27) lgkmcnt(0)
	v_mfma_f32_32x32x16_bf16 v[2:17], v[38:41], v[54:57], v[2:17]
	s_waitcnt vmcnt(26)
	v_mfma_f32_32x32x16_bf16 v[18:33], v[38:41], v[58:61], v[18:33]
	ds_read_b128 v[38:41], v207 offset:96
	s_waitcnt vmcnt(25) lgkmcnt(0)
	v_mfma_f32_32x32x16_bf16 v[2:17], v[38:41], v[62:65], v[2:17]
	s_waitcnt vmcnt(23)
	v_mfma_f32_32x32x16_bf16 v[18:33], v[38:41], v[70:73], v[18:33]
	ds_read_b128 v[38:41], v207 offset:128
	s_waitcnt lgkmcnt(0)
	v_mfma_f32_32x32x16_bf16 v[2:17], v[38:41], v[66:69], v[2:17]
	s_waitcnt vmcnt(22)
	v_mfma_f32_32x32x16_bf16 v[18:33], v[38:41], v[74:77], v[18:33]
	ds_read_b128 v[38:41], v207 offset:160
	s_waitcnt vmcnt(21) lgkmcnt(0)
	v_mfma_f32_32x32x16_bf16 v[2:17], v[38:41], v[78:81], v[2:17]
	s_waitcnt vmcnt(19)
	v_mfma_f32_32x32x16_bf16 v[18:33], v[38:41], v[86:89], v[18:33]
	ds_read_b128 v[38:41], v207 offset:192
	s_waitcnt lgkmcnt(0)
	v_mfma_f32_32x32x16_bf16 v[2:17], v[38:41], v[82:85], v[2:17]
	s_waitcnt vmcnt(18)
	v_mfma_f32_32x32x16_bf16 v[18:33], v[38:41], v[90:93], v[18:33]
	ds_read_b128 v[38:41], v207 offset:224
	s_waitcnt vmcnt(17) lgkmcnt(0)
	v_mfma_f32_32x32x16_bf16 v[2:17], v[38:41], v[94:97], v[2:17]
	s_waitcnt vmcnt(15)
	v_mfma_f32_32x32x16_bf16 v[18:33], v[38:41], v[102:105], v[18:33]
	ds_read_b128 v[38:41], v207 offset:256
	s_waitcnt lgkmcnt(0)
	v_mfma_f32_32x32x16_bf16 v[2:17], v[38:41], v[98:101], v[2:17]
	s_waitcnt vmcnt(14)
	v_mfma_f32_32x32x16_bf16 v[18:33], v[38:41], v[106:109], v[18:33]
	ds_read_b128 v[38:41], v207 offset:288
	s_waitcnt vmcnt(13) lgkmcnt(0)
	v_mfma_f32_32x32x16_bf16 v[2:17], v[38:41], v[110:113], v[2:17]
	s_waitcnt vmcnt(11)
	v_mfma_f32_32x32x16_bf16 v[18:33], v[38:41], v[118:121], v[18:33]
	ds_read_b128 v[38:41], v207 offset:320
	s_waitcnt lgkmcnt(0)
	v_mfma_f32_32x32x16_bf16 v[2:17], v[38:41], v[114:117], v[2:17]
	s_waitcnt vmcnt(10)
	v_mfma_f32_32x32x16_bf16 v[18:33], v[38:41], v[122:125], v[18:33]
	ds_read_b128 v[38:41], v207 offset:352
	s_waitcnt vmcnt(9) lgkmcnt(0)
	v_mfma_f32_32x32x16_bf16 v[2:17], v[38:41], v[126:129], v[2:17]
	s_waitcnt vmcnt(7)
	v_mfma_f32_32x32x16_bf16 v[18:33], v[38:41], v[134:137], v[18:33]
	ds_read_b128 v[38:41], v207 offset:384
	s_waitcnt lgkmcnt(0)
	v_mfma_f32_32x32x16_bf16 v[2:17], v[38:41], v[130:133], v[2:17]
	s_waitcnt vmcnt(6)
	v_mfma_f32_32x32x16_bf16 v[18:33], v[38:41], v[138:141], v[18:33]
	ds_read_b128 v[38:41], v207 offset:416
	s_waitcnt vmcnt(5) lgkmcnt(0)
	v_mfma_f32_32x32x16_bf16 v[2:17], v[38:41], v[142:145], v[2:17]
	s_waitcnt vmcnt(3)
	v_mfma_f32_32x32x16_bf16 v[18:33], v[38:41], v[150:153], v[18:33]
	ds_read_b128 v[38:41], v207 offset:448
	s_waitcnt lgkmcnt(0)
	v_mfma_f32_32x32x16_bf16 v[2:17], v[38:41], v[146:149], v[2:17]
	s_waitcnt vmcnt(2)
	v_mfma_f32_32x32x16_bf16 v[18:33], v[38:41], v[154:157], v[18:33]
	ds_read_b128 v[38:41], v207 offset:480
	s_waitcnt vmcnt(1) lgkmcnt(0)
	v_mfma_f32_32x32x16_bf16 v[2:17], v[38:41], v[158:161], v[2:17]
	s_waitcnt vmcnt(0)
	v_mfma_f32_32x32x16_bf16 v[18:33], v[38:41], v[178:181], v[18:33]
	s_nop 11
	ds_write2_b32 v192, v2, v18 offset1:32
	ds_write2_b32 v192, v3, v19 offset0:132 offset1:164
	ds_write2_b32 v208, v4, v20 offset0:8 offset1:40
	ds_write2_b32 v208, v5, v21 offset0:140 offset1:172
	ds_write2_b32 v209, v6, v22 offset0:32 offset1:64
	ds_write2_b32 v209, v7, v23 offset0:164 offset1:196
	ds_write2_b32 v211, v8, v24 offset0:40 offset1:72
	ds_write2_b32 v211, v9, v25 offset0:172 offset1:204
	ds_write2_b32 v212, v10, v26 offset0:64 offset1:96
	ds_write2_b32 v212, v11, v27 offset0:196 offset1:228
	v_add_u32_e32 v2, 0x2400, v192
	ds_write2_b32 v2, v12, v28 offset0:72 offset1:104
	ds_write2_b32 v2, v13, v29 offset0:204 offset1:236
	v_add_u32_e32 v2, 0x3000, v192
	ds_write2_b32 v2, v14, v30 offset0:96 offset1:128
	v_add_u32_e32 v2, 0x3200, v192
	ds_write2_b32 v2, v15, v31 offset0:100 offset1:132
	v_add_u32_e32 v2, 0x3400, v192
	ds_write2_b32 v2, v16, v32 offset0:104 offset1:136
	v_add_u32_e32 v2, 0x3600, v192
	ds_write2_b32 v2, v17, v33 offset0:108 offset1:140
	v_lshl_add_u64 v[2:3], s[6:7], 0, v[174:175]
	v_lshl_add_u64 v[2:3], v[2:3], 0, v[166:167]
	s_waitcnt lgkmcnt(0)
	s_barrier
	s_mov_b64 s[100:101], s[6:7]
	s_mul_i32 s98, s3, 0x6000
	s_add_u32 s98, s100, s98
	s_addc_u32 s99, s101, 0
	v_lshlrev_b32_e32 v225, 4, v210
	v_add_u32_e32 v226, 0x1000, v225
	v_add_u32_e32 v227, 0x2000, v225
	v_add_u32_e32 v228, 0x3000, v225
	v_add_u32_e32 v229, 0x4000, v225
	v_add_u32_e32 v230, 0x5000, v225
	global_load_dwordx4 v[66:69], v225, s[98:99]
	global_load_dwordx4 v[70:73], v225, s[98:99] offset:1024
	v_cndmask_b32_e64 v4, 0, 1, s[68:69]
	v_cmp_ne_u32_e64 s[0:1], 1, v4
	s_cbranch_vccnz .LBB0_561
	global_load_dwordx4 v[74:77], v225, s[98:99] offset:2048
	s_and_b64 vcc, exec, s[0:1]
	s_cbranch_vccnz .LBB0_563
	s_branch .LBB0_562

; __device__ __forceinline__ void s5_prompt(const Args& a, LAS unsigned char* lds, int b, int g, int tid, int lane, int wave) {
;     ...
;       for (int ks = 0; ks < 16; ++ks) if (ks < 2 * mt + 2) am[ks] = *(const bf16x8*)(mw + 16 * ks);
.LBB0_562:
	global_load_dwordx4 v[78:81], v225, s[98:99] offset:3072
.LBB0_563:
	v_cndmask_b32_e64 v4, 0, 1, s[70:71]
	v_cmp_ne_u32_e64 s[0:1], 1, v4
	s_andn2_b64 vcc, exec, s[70:71]
	s_cbranch_vccnz .LBB0_565
	global_load_dwordx4 v[82:85], v226, s[98:99]
	s_and_b64 vcc, exec, s[0:1]
	s_cbranch_vccnz .LBB0_567
	s_branch .LBB0_566

; __device__ __forceinline__ void s5_prompt(const Args& a, LAS unsigned char* lds, int b, int g, int tid, int lane, int wave) {
;     ...
;       for (int ks = 0; ks < 16; ++ks) if (ks < 2 * mt + 2) am[ks] = *(const bf16x8*)(mw + 16 * ks);
.LBB0_566:
	global_load_dwordx4 v[86:89], v226, s[98:99] offset:1024
.LBB0_567:
	v_cndmask_b32_e64 v4, 0, 1, s[72:73]
	v_cmp_ne_u32_e64 s[0:1], 1, v4
	s_andn2_b64 vcc, exec, s[72:73]
	s_cbranch_vccnz .LBB0_569
	global_load_dwordx4 v[90:93], v226, s[98:99] offset:2048
	s_and_b64 vcc, exec, s[0:1]
	s_cbranch_vccnz .LBB0_571
	s_branch .LBB0_570

; __device__ __forceinline__ void s5_prompt(const Args& a, LAS unsigned char* lds, int b, int g, int tid, int lane, int wave) {
;     ...
;       for (int ks = 0; ks < 16; ++ks) if (ks < 2 * mt + 2) am[ks] = *(const bf16x8*)(mw + 16 * ks);
.LBB0_570:
	global_load_dwordx4 v[94:97], v226, s[98:99] offset:3072
.LBB0_571:
	v_cndmask_b32_e64 v4, 0, 1, s[88:89]
	v_cmp_ne_u32_e64 s[0:1], 1, v4
	s_andn2_b64 vcc, exec, s[88:89]
	s_cbranch_vccnz .LBB0_573
	global_load_dwordx4 v[98:101], v227, s[98:99]
	s_and_b64 vcc, exec, s[0:1]
	s_cbranch_vccnz .LBB0_575
	s_branch .LBB0_574

; __device__ __forceinline__ void s5_prompt(const Args& a, LAS unsigned char* lds, int b, int g, int tid, int lane, int wave) {
;     ...
;       for (int ks = 0; ks < 16; ++ks) if (ks < 2 * mt + 2) am[ks] = *(const bf16x8*)(mw + 16 * ks);
.LBB0_574:
	global_load_dwordx4 v[102:105], v227, s[98:99] offset:1024
.LBB0_575:
	v_cndmask_b32_e64 v4, 0, 1, s[90:91]
	v_cmp_ne_u32_e64 s[0:1], 1, v4
	s_andn2_b64 vcc, exec, s[90:91]
	s_cbranch_vccnz .LBB0_577
	global_load_dwordx4 v[106:109], v227, s[98:99] offset:2048
	s_and_b64 vcc, exec, s[0:1]
	s_cbranch_vccnz .LBB0_579
	s_branch .LBB0_578

; __device__ __forceinline__ void s5_prompt(const Args& a, LAS unsigned char* lds, int b, int g, int tid, int lane, int wave) {
;     ...
;       for (int ks = 0; ks < 16; ++ks) if (ks < 2 * mt + 2) am[ks] = *(const bf16x8*)(mw + 16 * ks);
.LBB0_578:
	global_load_dwordx4 v[110:113], v227, s[98:99] offset:3072
.LBB0_579:
	v_cndmask_b32_e64 v4, 0, 1, s[92:93]
	v_cmp_ne_u32_e64 s[0:1], 1, v4
	s_andn2_b64 vcc, exec, s[92:93]
	s_cbranch_vccnz .LBB0_581
	global_load_dwordx4 v[114:117], v228, s[98:99]
	s_and_b64 vcc, exec, s[0:1]
	s_cbranch_vccnz .LBB0_583
	s_branch .LBB0_582

; __device__ __forceinline__ void s5_prompt(const Args& a, LAS unsigned char* lds, int b, int g, int tid, int lane, int wave) {
;     ...
;       for (int ks = 0; ks < 16; ++ks) if (ks < 2 * mt + 2) am[ks] = *(const bf16x8*)(mw + 16 * ks);
.LBB0_582:
	global_load_dwordx4 v[118:121], v228, s[98:99] offset:1024
.LBB0_583:
	v_cndmask_b32_e64 v4, 0, 1, s[94:95]
	v_cmp_ne_u32_e64 s[0:1], 1, v4
	s_andn2_b64 vcc, exec, s[94:95]
	s_cbranch_vccnz .LBB0_585
	global_load_dwordx4 v[122:125], v228, s[98:99] offset:2048
	s_and_b64 vcc, exec, s[0:1]
	s_cbranch_vccz .LBB0_586
	s_branch .LBB0_587

; #define LAS __attribute__((address_space(3)))
; __device__ __forceinline__ void s5_prompt(const Args& a, LAS unsigned char* lds, int b, int g, int tid, int lane, int wave) {
;     ...
;       for (int ks = 0; ks < 16; ++ks) if (ks < 2 * mt + 2) am[ks] = *(const bf16x8*)(mw + 16 * ks);
; #pragma unroll
;       for (int kq = 0; kq < 8; ++kq) am[16 + kq] = *(const bf16x8*)(mw + 256 + 16 * kq); }
;     if (wave == 0) {
;         const LAS float* zp = (const LAS float*)ZS + lane;
;         LAS unsigned short* sp = (LAS unsigned short*)ZS + lane;
;         float sr = 0.f, si = 0.f;
.LBB0_586:
	global_load_dwordx4 v[126:129], v228, s[98:99] offset:3072
.LBB0_587:
	global_load_dwordx4 v[130:133], v229, s[98:99]
	global_load_dwordx4 v[134:137], v229, s[98:99] offset:1024
	global_load_dwordx4 v[138:141], v229, s[98:99] offset:2048
	global_load_dwordx4 v[142:145], v229, s[98:99] offset:3072
	global_load_dwordx4 v[146:149], v230, s[98:99]
	global_load_dwordx4 v[150:153], v230, s[98:99] offset:1024
	global_load_dwordx4 v[154:157], v230, s[98:99] offset:2048
	global_load_dwordx4 v[158:161], v230, s[98:99] offset:3072
	v_cndmask_b32_e64 v2, 0, 1, s[18:19]
	v_cmp_ne_u32_e64 s[0:1], 1, v2
	s_andn2_b64 vcc, exec, s[18:19]
	s_cbranch_vccnz .LBB0_591
	v_mov_b32_e32 v2, 0
	v_mov_b32_e32 v35, v34
	v_mov_b32_e32 v37, v36
	s_mov_b32 s38, 16
	v_mov_b32_e32 v4, v193
	v_mov_b32_e32 v5, v194
	v_mov_b32_e32 v3, v2

; __device__ __forceinline__ void s5_prompt(const Args& a, LAS unsigned char* lds, int b, int g, int tid, int lane, int wave) {
;     ...
;         const int mt = pass ? 7 - wave : wave, n0 = 2 * pass;
;         const int nks = 2 * mt + 2;
;         const bf16_t* mw = MW + (size_t)(32 * mt + r32) * 384 + 8 * hh;
;         if (pass == 1) {
; #pragma unroll
;             for (int ks = 0; ks < 16; ++ks) if (ks < nks) am[ks] = *(const bf16x8*)(mw + 16 * ks);
.LBB0_596:
	s_andn2_b64 vcc, exec, s[6:7]
	s_cbranch_vccnz .LBB0_630
	s_mul_i32 s98, s78, 0x6000
	s_add_u32 s98, s100, s98
	s_addc_u32 s99, s101, 0
	v_lshl_or_b32 v2, s78, 5, v184
	v_mad_i64_i32 v[2:3], s[6:7], v2, s33, v[178:179]
	v_cndmask_b32_e64 v4, 0, 1, s[96:97]
	v_cmp_ne_u32_e64 s[6:7], 1, v4
	s_andn2_b64 vcc, exec, s[96:97]
	s_cbranch_vccnz .LBB0_613
	global_load_dwordx4 v[66:69], v225, s[98:99]
	s_and_b64 vcc, exec, s[6:7]
	s_cbranch_vccz .LBB0_614

; __device__ __forceinline__ void s5_prompt(const Args& a, LAS unsigned char* lds, int b, int g, int tid, int lane, int wave) {
;     ...
;             for (int ks = 0; ks < 16; ++ks) if (ks < nks) am[ks] = *(const bf16x8*)(mw + 16 * ks);
.LBB0_600:
	global_load_dwordx4 v[74:77], v225, s[98:99] offset:2048
	s_and_b64 vcc, exec, s[6:7]
	s_cbranch_vccz .LBB0_616

; __device__ __forceinline__ void s5_prompt(const Args& a, LAS unsigned char* lds, int b, int g, int tid, int lane, int wave) {
;     ...
;             for (int ks = 0; ks < 16; ++ks) if (ks < nks) am[ks] = *(const bf16x8*)(mw + 16 * ks);
.LBB0_602:
	global_load_dwordx4 v[82:85], v226, s[98:99]
	s_and_b64 vcc, exec, s[6:7]
	s_cbranch_vccz .LBB0_618

; __device__ __forceinline__ void s5_prompt(const Args& a, LAS unsigned char* lds, int b, int g, int tid, int lane, int wave) {
;     ...
;             for (int ks = 0; ks < 16; ++ks) if (ks < nks) am[ks] = *(const bf16x8*)(mw + 16 * ks);
.LBB0_604:
	global_load_dwordx4 v[90:93], v226, s[98:99] offset:2048
	s_and_b64 vcc, exec, s[6:7]
	s_cbranch_vccz .LBB0_620

; __device__ __forceinline__ void s5_prompt(const Args& a, LAS unsigned char* lds, int b, int g, int tid, int lane, int wave) {
;     ...
;             for (int ks = 0; ks < 16; ++ks) if (ks < nks) am[ks] = *(const bf16x8*)(mw + 16 * ks);
.LBB0_606:
	global_load_dwordx4 v[98:101], v227, s[98:99]
	s_and_b64 vcc, exec, s[6:7]
	s_cbranch_vccz .LBB0_622

; __device__ __forceinline__ void s5_prompt(const Args& a, LAS unsigned char* lds, int b, int g, int tid, int lane, int wave) {
;     ...
;             for (int ks = 0; ks < 16; ++ks) if (ks < nks) am[ks] = *(const bf16x8*)(mw + 16 * ks);
.LBB0_608:
	global_load_dwordx4 v[106:109], v227, s[98:99] offset:2048
	s_and_b64 vcc, exec, s[6:7]
	s_cbranch_vccz .LBB0_624

; __device__ __forceinline__ void s5_prompt(const Args& a, LAS unsigned char* lds, int b, int g, int tid, int lane, int wave) {
;     ...
;             for (int ks = 0; ks < 16; ++ks) if (ks < nks) am[ks] = *(const bf16x8*)(mw + 16 * ks);
.LBB0_610:
	global_load_dwordx4 v[114:117], v228, s[98:99]
	s_and_b64 vcc, exec, s[6:7]
	s_cbranch_vccz .LBB0_626

; __device__ __forceinline__ void s5_prompt(const Args& a, LAS unsigned char* lds, int b, int g, int tid, int lane, int wave) {
;     ...
;             for (int ks = 0; ks < 16; ++ks) if (ks < nks) am[ks] = *(const bf16x8*)(mw + 16 * ks);
.LBB0_612:
	global_load_dwordx4 v[122:125], v228, s[98:99] offset:2048
	s_and_b64 vcc, exec, s[0:1]
	s_cbranch_vccz .LBB0_628
	s_branch .LBB0_629

; __device__ __forceinline__ void s5_prompt(const Args& a, LAS unsigned char* lds, int b, int g, int tid, int lane, int wave) {
;     ...
;             for (int ks = 0; ks < 16; ++ks) if (ks < nks) am[ks] = *(const bf16x8*)(mw + 16 * ks);
.LBB0_614:
	global_load_dwordx4 v[70:73], v225, s[98:99] offset:1024
	v_cndmask_b32_e64 v4, 0, 1, s[86:87]
	v_cmp_ne_u32_e64 s[6:7], 1, v4
	s_andn2_b64 vcc, exec, s[86:87]
	s_cbranch_vccz .LBB0_600

; __device__ __forceinline__ void s5_prompt(const Args& a, LAS unsigned char* lds, int b, int g, int tid, int lane, int wave) {
;     ...
;             for (int ks = 0; ks < 16; ++ks) if (ks < nks) am[ks] = *(const bf16x8*)(mw + 16 * ks);
.LBB0_616:
	global_load_dwordx4 v[78:81], v225, s[98:99] offset:3072
	v_cndmask_b32_e64 v4, 0, 1, s[84:85]
	v_cmp_ne_u32_e64 s[6:7], 1, v4
	s_andn2_b64 vcc, exec, s[84:85]
	s_cbranch_vccz .LBB0_602

; __device__ __forceinline__ void s5_prompt(const Args& a, LAS unsigned char* lds, int b, int g, int tid, int lane, int wave) {
;     ...
;             for (int ks = 0; ks < 16; ++ks) if (ks < nks) am[ks] = *(const bf16x8*)(mw + 16 * ks);
.LBB0_618:
	global_load_dwordx4 v[86:89], v226, s[98:99] offset:1024
	v_cndmask_b32_e64 v4, 0, 1, s[4:5]
	v_cmp_ne_u32_e64 s[6:7], 1, v4
	s_andn2_b64 vcc, exec, s[4:5]
	s_cbranch_vccz .LBB0_604

; __device__ __forceinline__ void s5_prompt(const Args& a, LAS unsigned char* lds, int b, int g, int tid, int lane, int wave) {
;     ...
;             for (int ks = 0; ks < 16; ++ks) if (ks < nks) am[ks] = *(const bf16x8*)(mw + 16 * ks);
.LBB0_620:
	global_load_dwordx4 v[94:97], v226, s[98:99] offset:3072
	v_cndmask_b32_e64 v4, 0, 1, s[82:83]
	v_cmp_ne_u32_e64 s[6:7], 1, v4
	s_andn2_b64 vcc, exec, s[82:83]
	s_cbranch_vccz .LBB0_606

; __device__ __forceinline__ void s5_prompt(const Args& a, LAS unsigned char* lds, int b, int g, int tid, int lane, int wave) {
;     ...
;             for (int ks = 0; ks < 16; ++ks) if (ks < nks) am[ks] = *(const bf16x8*)(mw + 16 * ks);
.LBB0_622:
	global_load_dwordx4 v[102:105], v227, s[98:99] offset:1024
	v_cndmask_b32_e64 v4, 0, 1, s[30:31]
	v_cmp_ne_u32_e64 s[6:7], 1, v4
	s_andn2_b64 vcc, exec, s[30:31]
	s_cbranch_vccz .LBB0_608

; __device__ __forceinline__ void s5_prompt(const Args& a, LAS unsigned char* lds, int b, int g, int tid, int lane, int wave) {
;     ...
;             for (int ks = 0; ks < 16; ++ks) if (ks < nks) am[ks] = *(const bf16x8*)(mw + 16 * ks);
.LBB0_624:
	global_load_dwordx4 v[110:113], v227, s[98:99] offset:3072
	v_cndmask_b32_e64 v4, 0, 1, s[74:75]
	v_cmp_ne_u32_e64 s[6:7], 1, v4
	s_andn2_b64 vcc, exec, s[74:75]
	s_cbranch_vccz .LBB0_610

; __device__ __forceinline__ void s5_prompt(const Args& a, LAS unsigned char* lds, int b, int g, int tid, int lane, int wave) {
;     ...
;             for (int ks = 0; ks < 16; ++ks) if (ks < nks) am[ks] = *(const bf16x8*)(mw + 16 * ks);
.LBB0_626:
	global_load_dwordx4 v[118:121], v228, s[98:99] offset:1024
	s_and_b64 vcc, exec, s[0:1]
	s_cbranch_vccz .LBB0_612

; __device__ __forceinline__ void s5_prompt(const Args& a, LAS unsigned char* lds, int b, int g, int tid, int lane, int wave) {
;     ...
;             for (int kq = 0; kq < 8; ++kq) am[16 + kq] = *(const bf16x8*)(mw + 256 + 16 * kq);
.LBB0_629:
	global_load_dwordx4 v[130:133], v229, s[98:99]
	global_load_dwordx4 v[134:137], v229, s[98:99] offset:1024
	global_load_dwordx4 v[138:141], v229, s[98:99] offset:2048
	global_load_dwordx4 v[142:145], v229, s[98:99] offset:3072
	global_load_dwordx4 v[146:149], v230, s[98:99]
	global_load_dwordx4 v[150:153], v230, s[98:99] offset:1024
	global_load_dwordx4 v[154:157], v230, s[98:99] offset:2048
	global_load_dwordx4 v[158:161], v230, s[98:99] offset:3072

; __global__ void __launch_bounds__(NWAVES * 64, 2) hymba_fwd(Args args) {
	.amdhsa_kernel _Z9hymba_fwd4Args
		.amdhsa_group_segment_fixed_size 0
		.amdhsa_private_segment_fixed_size 0
		.amdhsa_kernarg_size 576
		.amdhsa_user_sgpr_count 2
		.amdhsa_user_sgpr_dispatch_ptr 0
		.amdhsa_user_sgpr_queue_ptr 0
		.amdhsa_user_sgpr_kernarg_segment_ptr 1
		.amdhsa_user_sgpr_dispatch_id 0
		.amdhsa_user_sgpr_kernarg_preload_length 0
		.amdhsa_user_sgpr_kernarg_preload_offset 0
		.amdhsa_user_sgpr_private_segment_size 0
		.amdhsa_uses_dynamic_stack 0
		.amdhsa_enable_private_segment 0
		.amdhsa_system_sgpr_workgroup_id_x 1
		.amdhsa_system_sgpr_workgroup_id_y 0
		.amdhsa_system_sgpr_workgroup_id_z 0
		.amdhsa_system_sgpr_workgroup_info 0
		.amdhsa_system_vgpr_workitem_id 0
		.amdhsa_next_free_vgpr 255
		.amdhsa_next_free_sgpr 102
		.amdhsa_accum_offset 256
		.amdhsa_reserve_vcc 1
		.amdhsa_float_round_mode_32 0
		.amdhsa_float_round_mode_16_64 0
		.amdhsa_float_denorm_mode_32 3
		.amdhsa_float_denorm_mode_16_64 3
		.amdhsa_dx10_clamp 1
		.amdhsa_ieee_mode 1
		.amdhsa_fp16_overflow 0
		.amdhsa_tg_split 0
		.amdhsa_exception_fp_ieee_invalid_op 0
		.amdhsa_exception_fp_denorm_src 0
		.amdhsa_exception_fp_ieee_div_zero 0
		.amdhsa_exception_fp_ieee_overflow 0
		.amdhsa_exception_fp_ieee_underflow 0
		.amdhsa_exception_fp_ieee_inexact 0
		.amdhsa_exception_int_div_zero 0
	.end_amdhsa_kernel

; __global__ void __launch_bounds__(NWAVES * 64, 2) hymba_fwd(Args args) {
amdhsa.kernels:
  - .agpr_count:     0
    .args:
      - .offset:         0
        .size:           320
        .value_kind:     by_value
      - .offset:         320
        .size:           4
        .value_kind:     hidden_block_count_x
      - .offset:         324
        .size:           4
        .value_kind:     hidden_block_count_y
      - .offset:         328
        .size:           4
        .value_kind:     hidden_block_count_z
      - .offset:         332
        .size:           2
        .value_kind:     hidden_group_size_x
      - .offset:         334
        .size:           2
        .value_kind:     hidden_group_size_y
      - .offset:         336
        .size:           2
        .value_kind:     hidden_group_size_z
      - .offset:         338
        .size:           2
        .value_kind:     hidden_remainder_x
      - .offset:         340
        .size:           2
        .value_kind:     hidden_remainder_y
      - .offset:         342
        .size:           2
        .value_kind:     hidden_remainder_z
      - .offset:         360
        .size:           8
        .value_kind:     hidden_global_offset_x
      - .offset:         368
        .size:           8
        .value_kind:     hidden_global_offset_y
      - .offset:         376
        .size:           8
        .value_kind:     hidden_global_offset_z
      - .offset:         384
        .size:           2
        .value_kind:     hidden_grid_dims
      - .offset:         440
        .size:           4
        .value_kind:     hidden_dynamic_lds_size
    .group_segment_fixed_size: 0
    .kernarg_segment_align: 8
    .kernarg_segment_size: 576
    .language:       OpenCL C
    .language_version:
      - 2
      - 0
    .max_flat_workgroup_size: 512
    .name:           _Z9hymba_fwd4Args
    .private_segment_fixed_size: 0
    .sgpr_count:     108
    .sgpr_spill_count: 65
    .symbol:         _Z9hymba_fwd4Args.kd
    .uniform_work_group_size: 1
    .uses_dynamic_stack: false
    .vgpr_count:     255
    .vgpr_spill_count: 0
    .wavefront_size: 64
